# nsa_main interior tiles: LDS-DMA issue of the prefetched tile moved behind the first 12 ds_reads of the tile (overlaps LDS latency), on top of v12
# baseline (speedup 1.0000x reference)
; template <int MODE> __device__ __forceinline__ void attn_branch(const bf16* __restrict__ Kbase, const bf16* __restrict__ VTbase, int kt_lo, int kt_hi, int tq0, int t, int h, int q, int tid, int wave, ...
;     ...
;     auto dma = [&](int kt, int buf) {
;         const char* kg = (const char*)Kbase + (size_t)kt * (64 * 128 * 2); const char* vg = (const char*)VTbase + kt * 128;
; #pragma unroll
;         for (int i = 0; i < 2; ++i) { const int n = 2 * wave + i;
;             __builtin_amdgcn_global_load_lds((const unsigned*)(kg + ((n >> 3) * 8192 + (n & 7) * 32) + kvo), (LAS unsigned*)(ldsl + buf * ATT_BUF + n * 1024), 16, 0, 0);
;             __builtin_amdgcn_global_load_lds((const unsigned*)(vg + ((size_t)(n >> 2) * (32 * SEQ * 2) + (n & 3) * 32) + vvo), (LAS unsigned*)(ldsl + buf * ATT_BUF + 16384 + n * 1024), 16, 0, 0); } };
;     const int lane16 = (h * 32 + q) * 16;
;     const int tlane = ATT_BTAB + ((0 - q) & 3) * (ATT_NEXT * 4) + 4 * (ATT_EOFF - ((0 - q) & 3));
;     ATT_BAR();
;     dma(kt_lo, 0);
;     if (kt_lo < kt_hi) { dma(kt_lo + 1, 1); asm volatile("s_waitcnt vmcnt(4)" ::: "memory"); } else asm volatile("s_waitcnt vmcnt(0)" ::: "memory");
;     ATT_BAR();
;     int buf = 0;
;     for (int kt = kt_lo; kt <= kt_hi; ++kt) {
;         const bool more = kt + 2 <= kt_hi;
;         if (more) dma(kt + 2, buf == 0 ? 2 : buf - 1);
;         bool need = 64 * kt <= tq0 + 31;
;         if (MODE == 1) need = need && (64 * kt + 63 >= tq0 - 511);
;         const bool sel = MODE == 0 ? ((selmask >> kt) & 1ull) != 0ull : true;
;         if (need && (MODE == 1 || __ballot(sel) != 0ull)) {
;             const LAS unsigned char* fq = ldsl + buf * ATT_BUF + lane16;
;             const int mind = tq0 - (64 * kt + 63), maxd = tq0 + 31 - 64 * kt;
;             const float msk = sel ? 1.f : 0.f;
;             const int d0 = t - 64 * kt - 4 * h;
;             if (MODE == 0) {
;                 const int nearf = __builtin_amdgcn_readfirstlane(mind < 128 ? 1 : 0);
;                 attn_tile<MODE, 3>(fq, ldsl + tlane - 4 * d0, msk, nearf, qf, O, lsum);
;             } else if (mind >= 128) {
;                 if (maxd <= 511) attn_tile<MODE, 0>(fq, ldsl, msk, 0, qf, O, lsum);
;                 else attn_tile<MODE, 2>(fq, ldsl, msk, d0 - 512, qf, O, lsum);
;             } else attn_tile<MODE, 1>(fq, ldsl + tlane - 4 * d0, msk, 0, qf, O, lsum);
.LBB0_1854:
	s_add_i32 s12, s21, 3
	s_cmp_le_i32 s12, s20
	s_cselect_b64 s[10:11], -1, 0
	s_cmp_gt_i32 s12, s20
	s_cbranch_scc1 .LBB0_1856
	s_cmp_le_i32 s34, s62
	s_cselect_b64 s[12:13], -1, 0
	s_add_i32 s15, s34, 63
	s_cmp_ge_i32 s15, s19
	s_cselect_b64 s[26:27], -1, 0
	s_and_b64 s[12:13], s[12:13], s[26:27]
	s_andn2_b64 vcc, exec, s[12:13]
	s_cbranch_vccnz .Lnsa_dma_now
	s_add_i32 s12, s35, 0xffffffa2
	s_cmpk_lt_i32 s12, 0x80
	s_cbranch_scc1 .LBB0_1856
.Lnsa_dma_now:
	s_lshl_b32 s13, s14, 15
	s_ashr_i32 s12, s36, 31
	s_addk_i32 s13, 0x8000
	s_cmp_lg_u32 s14, 0
	s_cselect_b32 s13, s13, 0x10000
	s_add_i32 s15, s13, 0
	s_add_i32 s16, s15, s54
	s_add_u32 s26, s17, s36
	s_addc_u32 s27, s18, s12
	s_mov_b32 m0, s16
	s_add_u32 s12, s26, s55
	global_load_lds_dwordx4 v[194:195], off
	s_addc_u32 s13, s27, 0
	s_add_i32 m0, s16, 0x4000
	s_add_i32 s15, s15, s56
	v_lshl_add_u64 v[68:69], s[12:13], 0, v[188:189]
	s_add_u32 s12, s26, s57
	global_load_lds_dwordx4 v[68:69], off
	s_mov_b32 m0, s15
	s_addc_u32 s13, s27, 0
	global_load_lds_dwordx4 v[192:193], off
	v_lshl_add_u64 v[68:69], s[12:13], 0, v[188:189]
	s_add_i32 m0, s15, 0x4000
	s_nop 0
	global_load_lds_dwordx4 v[68:69], off
.LBB0_1856:
	s_cmp_le_i32 s34, s62
	s_cselect_b64 s[12:13], -1, 0
	s_add_i32 s15, s34, 63
	s_cmp_ge_i32 s15, s19
	s_cselect_b64 s[26:27], -1, 0
	s_and_b64 s[12:13], s[12:13], s[26:27]
	s_andn2_b64 vcc, exec, s[12:13]
	s_cbranch_vccnz .LBB0_1866
	s_add_i32 s12, s35, 0xffffffa2
	v_lshl_add_u32 v2, s14, 15, v1
	s_cmpk_lt_i32 s12, 0x80
	s_mov_b64 s[12:13], -1
	s_cbranch_scc0 .LBB0_1859
	ds_read_b128 v[68:71], v183
	ds_read_b128 v[72:75], v183 offset:32
	ds_read_b128 v[76:79], v183 offset:64
	ds_read_b128 v[80:83], v183 offset:96
	ds_read_b128 v[84:87], v2
	ds_read_b128 v[88:91], v2 offset:1024
	ds_read_b128 v[92:95], v2 offset:2048
	ds_read_b128 v[96:99], v2 offset:3072
	ds_read_b128 v[108:111], v2 offset:4096
	ds_read_b128 v[112:115], v2 offset:5120
	ds_read_b128 v[116:119], v2 offset:6144
	ds_read_b128 v[120:123], v2 offset:7168
	s_andn2_b64 vcc, exec, s[10:11]
	s_cbranch_vccnz .Lnsa_a_nodma
	s_lshl_b32 s13, s14, 15
	s_ashr_i32 s12, s36, 31
	s_addk_i32 s13, 0x8000
	s_cmp_lg_u32 s14, 0
	s_cselect_b32 s13, s13, 0x10000
	s_add_i32 s15, s13, 0
	s_add_i32 s16, s15, s54
	s_add_u32 s26, s17, s36
	s_addc_u32 s27, s18, s12
	s_mov_b32 m0, s16
	s_add_u32 s12, s26, s55
	global_load_lds_dwordx4 v[194:195], off
	s_addc_u32 s13, s27, 0
	s_add_i32 m0, s16, 0x4000
	s_add_i32 s15, s15, s56
	v_lshl_add_u64 v[164:165], s[12:13], 0, v[188:189]
	s_add_u32 s12, s26, s57
	global_load_lds_dwordx4 v[164:165], off
	s_mov_b32 m0, s15
	s_addc_u32 s13, s27, 0
	global_load_lds_dwordx4 v[192:193], off
	v_lshl_add_u64 v[164:165], s[12:13], 0, v[188:189]
	s_add_i32 m0, s15, 0x4000
	s_nop 0
	global_load_lds_dwordx4 v[164:165], off
; #define MFMA32(a, b, c) __builtin_amdgcn_mfma_f32_32x32x16_bf16((a), (b), (c), 0, 0, 0)
; template <int MODE, int KIND> __device__ __forceinline__ void attn_tile(const LAS unsigned char* fq, const LAS unsigned char* tb, float msk, int dlim, const bf16x8 (&qf)[8], f32x16 (&O)[4], float& lsum) {
;     ...
;     u32x4 fa[4], fb[4]; f32x16 S0, S1; bf16x8 pb0[2], pb1[2];
;     ATT_SINIT(S0, 0);
; #pragma unroll
;     for (int s = 0; s < 4; ++s) fa[s] = ATT_KF(0, s);
;     ATT_SB();
; #pragma unroll
;     for (int s = 0; s < 4; ++s) fb[s] = ATT_KF(0, 4 + s);
; #pragma unroll
;     for (int s = 0; s < 4; ++s) S0 = MFMA32(ATT_BF(fa[s]), qf[s], S0);
;     ATT_SB();
; #pragma unroll
;     for (int s = 0; s < 4; ++s) fa[s] = ATT_KF(1, s);
;     ATT_SINIT(S1, 1);
; #pragma unroll
;     for (int s = 0; s < 4; ++s) S0 = MFMA32(ATT_BF(fb[s]), qf[4 + s], S0);
;     ATT_SB();
; #pragma unroll
;     for (int s = 0; s < 4; ++s) fb[s] = ATT_KF(1, 4 + s);
; #pragma unroll
;     for (int s = 0; s < 4; ++s) S1 = MFMA32(ATT_BF(fa[s]), qf[s], S1);
;     ATT_SB();
;     fa[0] = ATT_VF(0, 0); fa[1] = ATT_VF(0, 1); fa[2] = ATT_VF(1, 0); fa[3] = ATT_VF(1, 1);
; #pragma unroll
;     for (int s = 0; s < 4; ++s) S1 = MFMA32(ATT_BF(fb[s]), qf[4 + s], S1);
;     ATT_EXP(S0, 0, pb0);
;     ATT_SB();
;     fb[0] = ATT_VF(2, 0); fb[1] = ATT_VF(2, 1); fb[2] = ATT_VF(3, 0); fb[3] = ATT_VF(3, 1);
;     O[0] = MFMA32(ATT_BF(fa[0]), pb0[0], O[0]); O[0] = MFMA32(ATT_BF(fa[1]), pb0[1], O[0]); O[1] = MFMA32(ATT_BF(fa[2]), pb0[0], O[1]); O[1] = MFMA32(ATT_BF(fa[3]), pb0[1], O[1]);
;     ATT_EXP(S1, 1, pb1);
;     ATT_SB();
;     fa[0] = ATT_VF(0, 2); fa[1] = ATT_VF(0, 3); fa[2] = ATT_VF(1, 2); fa[3] = ATT_VF(1, 3);
;     O[2] = MFMA32(ATT_BF(fb[0]), pb0[0], O[2]); O[2] = MFMA32(ATT_BF(fb[1]), pb0[1], O[2]); O[3] = MFMA32(ATT_BF(fb[2]), pb0[0], O[3]); O[3] = MFMA32(ATT_BF(fb[3]), pb0[1], O[3]);
;     ATT_SB();
;     fb[0] = ATT_VF(2, 2); fb[1] = ATT_VF(2, 3); fb[2] = ATT_VF(3, 2); fb[3] = ATT_VF(3, 3);
;     O[0] = MFMA32(ATT_BF(fa[0]), pb1[0], O[0]); O[0] = MFMA32(ATT_BF(fa[1]), pb1[1], O[0]); O[1] = MFMA32(ATT_BF(fa[2]), pb1[0], O[1]); O[1] = MFMA32(ATT_BF(fa[3]), pb1[1], O[1]);
;     ATT_SB();
;     O[2] = MFMA32(ATT_BF(fb[0]), pb1[0], O[2]); O[2] = MFMA32(ATT_BF(fb[1]), pb1[1], O[2]); O[3] = MFMA32(ATT_BF(fb[2]), pb1[0], O[3]); O[3] = MFMA32(ATT_BF(fb[3]), pb1[1], O[3]);
.Lnsa_a_nodma:
	s_waitcnt lgkmcnt(7)
	v_mfma_f32_32x32x16_bf16 v[68:83], v[84:87], v[132:135], v[68:83]
	ds_read_b128 v[124:127], v2 offset:8192
	ds_read_b128 v[128:131], v2 offset:9216
	ds_read_b128 v[164:167], v2 offset:10240
	ds_read_b128 v[168:171], v2 offset:11264
	s_waitcnt lgkmcnt(10)
	v_mfma_f32_32x32x16_bf16 v[68:83], v[88:91], v[136:139], v[68:83]
	s_waitcnt lgkmcnt(9)
	v_mfma_f32_32x32x16_bf16 v[68:83], v[92:95], v[140:143], v[68:83]
	s_waitcnt lgkmcnt(8)
	v_mfma_f32_32x32x16_bf16 v[68:83], v[96:99], v[144:147], v[68:83]
	ds_read_b128 v[92:95], v183 offset:128
	ds_read_b128 v[96:99], v183 offset:160
	ds_read_b128 v[100:103], v183 offset:192
	ds_read_b128 v[104:107], v183 offset:224
	s_waitcnt lgkmcnt(0)
	v_mfma_f32_32x32x16_bf16 v[92:107], v[124:127], v[132:135], v[92:107]
	v_mfma_f32_32x32x16_bf16 v[92:107], v[128:131], v[136:139], v[92:107]
	v_mfma_f32_32x32x16_bf16 v[68:83], v[108:111], v[148:151], v[68:83]
	v_mfma_f32_32x32x16_bf16 v[92:107], v[164:167], v[140:143], v[92:107]
	v_mfma_f32_32x32x16_bf16 v[68:83], v[112:115], v[152:155], v[68:83]
	ds_read_b128 v[84:87], v2 offset:12288
	ds_read_b128 v[88:91], v2 offset:13312
	ds_read_b128 v[108:111], v2 offset:14336
	ds_read_b128 v[112:115], v2 offset:15360
	v_mfma_f32_32x32x16_bf16 v[92:107], v[168:171], v[144:147], v[92:107]
	v_mfma_f32_32x32x16_bf16 v[68:83], v[116:119], v[156:159], v[68:83]
	s_waitcnt lgkmcnt(0)
	v_mfma_f32_32x32x16_bf16 v[92:107], v[84:87], v[148:151], v[92:107]
	ds_read_b128 v[116:119], v2 offset:16384
	ds_read_b128 v[124:127], v2 offset:17408
	ds_read_b128 v[128:131], v2 offset:20480
	ds_read_b128 v[164:167], v2 offset:21504
	v_mfma_f32_32x32x16_bf16 v[68:83], v[120:123], v[160:163], v[68:83]
	v_mfma_f32_32x32x16_bf16 v[92:107], v[88:91], v[152:155], v[92:107]
	s_nop 10
	v_exp_f32_e32 v68, v68
	v_exp_f32_e32 v69, v69
	v_exp_f32_e32 v70, v70
	v_exp_f32_e32 v71, v71
	v_exp_f32_e32 v72, v72
	v_add_f32_e32 v120, v197, v68
	v_exp_f32_e32 v73, v73
	v_mfma_f32_32x32x16_bf16 v[92:107], v[108:111], v[156:159], v[92:107]
	v_add_f32_e32 v120, v69, v120
	v_exp_f32_e32 v74, v74
	v_add_f32_e32 v120, v70, v120
	v_add_f32_e32 v120, v71, v120
	v_exp_f32_e32 v75, v75
	v_add_f32_e32 v120, v72, v120
	v_exp_f32_e32 v76, v76
	v_add_f32_e32 v120, v73, v120
	v_exp_f32_e32 v77, v77
	v_add_f32_e32 v120, v74, v120
	v_exp_f32_e32 v78, v78
	v_add_f32_e32 v120, v75, v120
	v_exp_f32_e32 v79, v79
	v_add_f32_e32 v84, v76, v120
	v_exp_f32_e32 v80, v80
	v_mfma_f32_32x32x16_bf16 v[92:107], v[112:115], v[160:163], v[92:107]
	v_add_f32_e32 v84, v77, v84
	v_exp_f32_e32 v81, v81
	v_add_f32_e32 v84, v78, v84
	v_exp_f32_e32 v82, v82
	v_add_f32_e32 v84, v79, v84
	v_exp_f32_e32 v83, v83
	v_add_f32_e32 v84, v80, v84
	v_add_f32_e32 v84, v81, v84
	v_add_f32_e32 v84, v82, v84
	v_add_f32_e32 v84, v83, v84
	v_cvt_pk_bf16_f32 v168, v68, v69
	v_cvt_pk_bf16_f32 v169, v70, v71
	v_cvt_pk_bf16_f32 v170, v72, v73
	v_cvt_pk_bf16_f32 v171, v74, v75
	v_cvt_pk_bf16_f32 v172, v76, v77
	v_cvt_pk_bf16_f32 v173, v78, v79
	v_cvt_pk_bf16_f32 v174, v80, v81
	v_cvt_pk_bf16_f32 v175, v82, v83
	v_exp_f32_e32 v108, v92
	v_exp_f32_e32 v109, v93
	v_exp_f32_e32 v110, v94
	v_exp_f32_e32 v111, v95
	v_add_f32_e32 v84, v108, v84
	v_exp_f32_e32 v112, v96
	v_add_f32_e32 v84, v109, v84
	v_exp_f32_e32 v113, v97
	v_add_f32_e32 v84, v110, v84
	v_exp_f32_e32 v114, v98
	v_add_f32_e32 v84, v111, v84
	v_add_f32_e32 v84, v112, v84
	v_add_f32_e32 v84, v113, v84
	s_waitcnt lgkmcnt(0)
	v_mfma_f32_32x32x16_bf16 v[52:67], v[116:119], v[168:171], v[52:67]
	v_exp_f32_e32 v115, v99
	v_add_f32_e32 v116, v114, v84
	v_exp_f32_e32 v100, v100
	v_exp_f32_e32 v101, v101
	v_exp_f32_e32 v102, v102
	v_add_f32_e32 v116, v115, v116
	v_exp_f32_e32 v103, v103
	v_mfma_f32_32x32x16_bf16 v[36:51], v[128:131], v[168:171], v[36:51]
	v_add_f32_e32 v116, v100, v116
	v_exp_f32_e32 v104, v104
	v_add_f32_e32 v116, v101, v116
	v_exp_f32_e32 v105, v105
	v_add_f32_e32 v116, v102, v116
	v_exp_f32_e32 v106, v106
	ds_read_b128 v[120:123], v2 offset:24576
	ds_read_b128 v[176:179], v2 offset:25600
	v_mfma_f32_32x32x16_bf16 v[52:67], v[124:127], v[172:175], v[52:67]
	ds_read_b128 v[198:201], v2 offset:28672
	ds_read_b128 v[202:205], v2 offset:29696
	v_add_f32_e32 v116, v103, v116
	v_exp_f32_e32 v107, v107
	v_add_f32_e32 v116, v104, v116
	v_add_f32_e32 v116, v105, v116
	v_add_f32_e32 v116, v106, v116
	v_add_f32_e32 v184, v107, v116
	v_mfma_f32_32x32x16_bf16 v[36:51], v[164:167], v[172:175], v[36:51]
	v_cvt_pk_bf16_f32 v164, v108, v109
	v_cvt_pk_bf16_f32 v165, v110, v111
	v_cvt_pk_bf16_f32 v166, v112, v113
	v_cvt_pk_bf16_f32 v167, v114, v115
	v_cvt_pk_bf16_f32 v206, v100, v101
	v_cvt_pk_bf16_f32 v207, v102, v103
	v_cvt_pk_bf16_f32 v208, v104, v105
	v_cvt_pk_bf16_f32 v209, v106, v107
	s_waitcnt lgkmcnt(0)
	v_mfma_f32_32x32x16_bf16 v[20:35], v[120:123], v[168:171], v[20:35]
	v_mfma_f32_32x32x16_bf16 v[4:19], v[198:201], v[168:171], v[4:19]
	v_mfma_f32_32x32x16_bf16 v[20:35], v[176:179], v[172:175], v[20:35]
	ds_read_b128 v[168:171], v2 offset:18432
	ds_read_b128 v[176:179], v2 offset:19456
	ds_read_b128 v[198:201], v2 offset:22528
	ds_read_b128 v[210:213], v2 offset:23552
	v_mfma_f32_32x32x16_bf16 v[4:19], v[202:205], v[172:175], v[4:19]
	s_waitcnt lgkmcnt(0)
	v_mfma_f32_32x32x16_bf16 v[52:67], v[168:171], v[164:167], v[52:67]
	v_mfma_f32_32x32x16_bf16 v[36:51], v[198:201], v[164:167], v[36:51]
	v_mfma_f32_32x32x16_bf16 v[52:67], v[176:179], v[206:209], v[52:67]
	ds_read_b128 v[168:171], v2 offset:26624
	ds_read_b128 v[172:175], v2 offset:27648
	ds_read_b128 v[176:179], v2 offset:30720
	ds_read_b128 v[198:201], v2 offset:31744
	v_mfma_f32_32x32x16_bf16 v[36:51], v[210:213], v[206:209], v[36:51]
	s_waitcnt lgkmcnt(0)
	v_mfma_f32_32x32x16_bf16 v[20:35], v[168:171], v[164:167], v[20:35]
	v_mfma_f32_32x32x16_bf16 v[4:19], v[176:179], v[164:167], v[4:19]
	v_mfma_f32_32x32x16_bf16 v[20:35], v[172:175], v[206:209], v[20:35]
	v_mfma_f32_32x32x16_bf16 v[4:19], v[198:201], v[206:209], v[4:19]
	s_mov_b64 s[12:13], 0
